# phase +3 queue: next item index requested (atomic) right after the current one is accepted, consumed at the next trip, so the round trip runs under the item
# speedup vs baseline: 1.0036x; 1.0002x over previous
; #define LAS __attribute__((address_space(3)))
; __global__ void __launch_bounds__(512, 2) mk_fwd(Args args) {
;     ...
;                     unsigned* actr = (unsigned*)(ws + WS_CTL) + CW_Q + 64 * (l * 16 + 2 + (u >> 5));
;                     volatile LAS int* qslot = (volatile LAS int*)(F.lds + LDS_CTL_OFF + 64);
;                     for (;;) {
;                         if (F.tid == 0) *qslot = (int)__hip_atomic_fetch_add(actr, 1u, __ATOMIC_RELAXED, __HIP_MEMORY_SCOPE_AGENT);
;                         __syncthreads(); const int qi = __builtin_amdgcn_readfirstlane(*qslot); __syncthreads();
.LBB0_1030:
	s_lshl_b32 s0, s66, 10
	v_readlane_b32 s1, v253, 2
	s_add_i32 s0, s0, s1
	s_ashr_i32 s1, s0, 31
	s_lshl_b64 s[0:1], s[0:1], 2
	v_readlane_b32 s2, v251, 50
	s_add_u32 s8, s2, s0
	v_readlane_b32 s0, v251, 51
	s_addc_u32 s9, s0, s1
	s_and_saveexec_b64 s[0:1], s[74:75]
	s_cbranch_execz .Lq3p_skip0
	v_mov_b32_e32 v164, 1
	s_nop 0
	global_atomic_add v164, v35, v164, s[8:9] sc0
.Lq3p_skip0:
	s_mov_b64 exec, s[0:1]
	s_branch .LBB0_1033

; __global__ void __launch_bounds__(512, 2) mk_fwd(Args args) {
;     ...
;                     for (;;) {
;                         if (F.tid == 0) *qslot = (int)__hip_atomic_fetch_add(actr, 1u, __ATOMIC_RELAXED, __HIP_MEMORY_SCOPE_AGENT);
;                         __syncthreads(); const int qi = __builtin_amdgcn_readfirstlane(*qslot); __syncthreads();
;                         if (qi >= 112) break;
.LBB0_1033:
	s_and_saveexec_b64 s[0:1], s[74:75]
	s_cbranch_execz .LBB0_1037
	s_waitcnt vmcnt(0)
	v_readfirstlane_b32 s2, v164
	v_mov_b32_e32 v2, s72
	s_nop 0
	v_mov_b32_e32 v1, s2
	ds_write_b32 v2, v1
.LBB0_1037:
	s_or_b64 exec, exec, s[0:1]
	v_mov_b32_e32 v1, s72
	s_waitcnt vmcnt(0) lgkmcnt(0)
	s_barrier
	ds_read_b32 v1, v1
	s_mov_b64 s[0:1], -1
	s_waitcnt lgkmcnt(0)
	s_barrier
	v_readfirstlane_b32 s2, v1
	s_cmpk_gt_i32 s2, 0x6f
	s_cbranch_scc1 .LBB0_1032
	s_and_saveexec_b64 s[0:1], s[74:75]
	s_cbranch_execz .Lq3p_skip1
	v_mov_b32_e32 v164, 1
	s_nop 0
	global_atomic_add v164, v35, v164, s[8:9] sc0
.Lq3p_skip1:
	s_mov_b64 exec, s[0:1]
	s_mov_b32 s12, s66
	s_mov_b64 s[10:11], s[62:63]
	s_mov_b32 s18, s94
	v_mov_b32_e32 v122, v210
	s_mov_b32 s0, s97
	v_mov_b32_e32 v1, v0
	s_mul_hi_i32 s0, s2, 0x92492493
	s_add_i32 s0, s0, s2
	s_lshr_b32 s1, s0, 31
	s_ashr_i32 s13, s0, 2
	s_add_i32 s13, s13, s1
	s_mul_i32 s0, s13, 7
	s_sub_i32 s14, s2, s0
	s_cmp_lt_i32 s14, 3
	s_cbranch_scc1 .LBB0_1041
	s_cmp_gt_i32 s14, 4
	s_cbranch_scc0 .LBB0_1042
	s_cmp_lg_u32 s14, 5
	s_mov_b64 s[0:1], -1
	s_cselect_b64 s[2:3], -1, 0
	s_cbranch_execz .LBB0_1043
	s_branch .LBB0_1044
